# attention: K/V staging waits counted (vmcnt 7..4) so tile u+2 loads stay in flight across the tile
# speedup vs baseline: 1.0090x; 1.0048x over previous
; #define ATT_LOAD(u_, KR, VR) do { const long _o = (long)((u_) >> 2) * (28L << 16) + ((u_) & 1) * 32768 + (((u_) >> 1) & 1) * 4096; _Pragma("unroll") for (int _i = 0; _i < 2; ++_i) { \
;         KR[_i] = *(const u32x4*)(kb0 + _o + _i * 16384); VR[_i] = *(const u32x4*)(vb0 + _o + _i * 16384); } } while (0)
; #define ATT_STORE(buf_, KR, VR) do { _Pragma("unroll") for (int _i = 0; _i < 2; ++_i) { const unsigned ob_ = off_b(srow, sch + 8 * _i); \
;         *(LAS u32x4*)(lds + (buf_) * 32768 + ob_) = KR[_i]; *(LAS u32x4*)(lds + (buf_) * 32768 + 16384 + ob_) = VR[_i]; } } while (0)
; __device__ void attn_quad(const bf16_t* proj, const float* rel_bias, bf16_t* ycat, int quad, LAS unsigned char* lds, const int WID) {
;     ...
;         ATT_STORE(buf ^ 1, kr1, vr1);
;         __syncthreads(); buf ^= 1;
;         if (u + 3 < 12) ATT_LOAD(u + 3, kr1, vr1);
.LBB0_365:
	s_cmp_gt_u32 s74, 8
	s_cbranch_scc1 .Latt_st1_last
	s_waitcnt vmcnt(7)
	ds_write_b128 v185, v[116:119] offset:32768
	s_waitcnt vmcnt(6)
	ds_write_b128 v185, v[120:123] offset:49152
	s_waitcnt vmcnt(5)
	ds_write_b128 v186, v[124:127] offset:32768
	s_waitcnt vmcnt(4)
	ds_write_b128 v186, v[128:131] offset:49152
	s_branch .Latt_st1_done
.Latt_st1_last:
	s_waitcnt vmcnt(3)
	ds_write_b128 v185, v[116:119] offset:32768
	s_waitcnt vmcnt(2)
	ds_write_b128 v185, v[120:123] offset:49152
	s_waitcnt vmcnt(1)
	ds_write_b128 v186, v[124:127] offset:32768
	s_waitcnt vmcnt(0)
	ds_write_b128 v186, v[128:131] offset:49152
.Latt_st1_done:
	s_waitcnt lgkmcnt(0)
	s_barrier
	s_cbranch_scc1 .LBB0_367
	s_lshr_b32 s10, s63, 2
	s_mul_i32 s10, s10, 0x1c0000
	s_and_b32 s11, s70, 0x1000
	s_or_b32 s10, s10, s11
	s_or_b32 s40, s10, 0x8000
	s_lshl_b64 s[10:11], s[40:41], 1
	v_lshl_add_u64 v[2:3], v[168:169], 0, s[10:11]
	v_lshl_add_u64 v[124:125], v[170:171], 0, s[10:11]
	global_load_dwordx4 v[116:119], v[2:3], off
	global_load_dwordx4 v[120:123], v[124:125], off
	v_add_co_u32_e32 v2, vcc, 0x8000, v2
	s_nop 1
	v_addc_co_u32_e32 v3, vcc, 0, v3, vcc
	v_add_co_u32_e32 v128, vcc, 0x8000, v124
	s_nop 1
	v_addc_co_u32_e32 v129, vcc, 0, v125, vcc
	global_load_dwordx4 v[124:127], v[2:3], off
	s_nop 0
	global_load_dwordx4 v[128:131], v[128:129], off

; #define ATT_STORE(buf_, KR, VR) do { _Pragma("unroll") for (int _i = 0; _i < 2; ++_i) { const unsigned ob_ = off_b(srow, sch + 8 * _i); \
;         *(LAS u32x4*)(lds + (buf_) * 32768 + ob_) = KR[_i]; *(LAS u32x4*)(lds + (buf_) * 32768 + 16384 + ob_) = VR[_i]; } } while (0)
; __device__ void attn_quad(const bf16_t* proj, const float* rel_bias, bf16_t* ycat, int quad, LAS unsigned char* lds, const int WID) {
;     ...
;         if (u + 2 < 12) ATT_STORE(buf ^ 1, kr0, vr0);
.LBB0_514:
	s_waitcnt vmcnt(7)
	ds_write_b128 v185, v[44:47]
	s_waitcnt vmcnt(6)
	ds_write_b128 v185, v[56:59] offset:16384
	s_waitcnt vmcnt(5)
	ds_write_b128 v186, v[68:71]
	s_waitcnt vmcnt(4)
	ds_write_b128 v186, v[72:75] offset:16384
	s_branch .LBB0_232
